# flash loops: s_setprio 1 over the QK^T MFMA cluster, s_setprio 0 before the softmax section
# speedup vs baseline: 1.0090x; 1.0090x over previous
; #define MFMA(a, b, c) __builtin_amdgcn_mfma_f32_32x32x16_bf16((a), (b), (c), 0, 0, 0)
; DI int crow(int i, int h) { return (i & 3) + 8 * (i >> 2) + 4 * h; }
; template <int DK, int DV, int MODE>
; DI void fa_qk(f32x16 (&S)[2], const bf16x8 (&q)[DK / 16], const char* base, int lr, int lh) {
;   using C = FA<DK, DV>;
; #pragma unroll
;   for (int ks = 0; ks < 2; ++ks) {
; #pragma unroll
;     for (int kk = 0; kk < DK / 16; ++kk) {
;       const bf16x8 kf = *(const bf16x8*)(base + (ks * 32 + lr) * C::KSTR + (kk * 2 + lh) * 16);
;       if (kk == 0) {
; #pragma unroll
;         for (int i = 0; i < 16; ++i) S[ks][i] = 0.f;
;       }
;       S[ks] = MFMA(kf, q[kk], S[ks]);
;     }
;   }
; }
;   using C = FA<DK, DV>;
;   bool selbit = true;
;   bool need_mask = false;
;   if (MODE != 0) need_mask = (kb * 64 + 63 > wave_qmax - 31);
;   if (MODE == 2) selbit = (sel >> kb) & 1ull;
;   if (MODE == 3) need_mask = need_mask || (kb * 64 <= wave_qmax - 512);
;   const float c2 = scale * 1.4426950408889634f;
;   if (need_mask) {
; #pragma unroll
;     for (int ks = 0; ks < 2; ++ks)
; #pragma unroll
;       for (int i = 0; i < 16; ++i) {
;         const int key = kb * 64 + ks * 32 + crow(i, lh);
;         bool valid = key <= qpos;
;         if (MODE == 2) valid = valid && selbit;
;         if (MODE == 3) valid = valid && (qpos - key < 512);
;         S[ks][i] = valid ? S[ks][i] : -1e30f;
;       }
.LBB0_374:
	v_cmp_le_i32_e32 vcc, s20, v110
	s_and_saveexec_b64 s[10:11], vcc
	s_cbranch_execz .LBB0_363
	s_add_i32 s6, s6, 0
	v_add3_u32 v104, s6, v112, v111
	ds_read_b128 v[34:37], v104
	ds_read_b128 v[38:41], v104 offset:32
	ds_read_b128 v[42:45], v104 offset:64
	ds_read_b128 v[46:49], v104 offset:96
	ds_read_b128 v[118:121], v104 offset:128
	ds_read_b128 v[122:125], v104 offset:160
	ds_read_b128 v[216:219], v104 offset:6656
	ds_read_b128 v[220:223], v104 offset:6688
	ds_read_b128 v[224:227], v104 offset:6720
	ds_read_b128 v[228:231], v104 offset:6752
	ds_read_b128 v[232:235], v104 offset:6784
	ds_read_b128 v[236:239], v104 offset:6816
	s_add_i32 s7, s20, 63
	v_cmp_gt_i32_e64 s[8:9], s7, v106
	v_add3_u32 v130, s6, v114, v115
	v_add_u32_e32 v131, 0x3000, v130
	v_add_u32_e32 v130, 0x4000, v130
	s_setprio 1
	s_waitcnt lgkmcnt(11)
	v_mfma_f32_32x32x16_bf16 v[50:65], v[34:37], v[82:85], 0
	s_waitcnt lgkmcnt(10)
	v_mfma_f32_32x32x16_bf16 v[50:65], v[38:41], v[66:69], v[50:65]
	s_waitcnt lgkmcnt(9)
	v_mfma_f32_32x32x16_bf16 v[50:65], v[42:45], v[70:73], v[50:65]
	s_waitcnt lgkmcnt(8)
	v_mfma_f32_32x32x16_bf16 v[50:65], v[46:49], v[74:77], v[50:65]
	s_waitcnt lgkmcnt(7)
	v_mfma_f32_32x32x16_bf16 v[50:65], v[118:121], v[78:81], v[50:65]
	s_waitcnt lgkmcnt(6)
	v_mfma_f32_32x32x16_bf16 v[50:65], v[122:125], v[86:89], v[50:65]
	s_waitcnt lgkmcnt(5)
	v_mfma_f32_32x32x16_bf16 v[34:49], v[216:219], v[82:85], 0
	s_waitcnt lgkmcnt(4)
	v_mfma_f32_32x32x16_bf16 v[34:49], v[220:223], v[66:69], v[34:49]
	s_waitcnt lgkmcnt(3)
	v_mfma_f32_32x32x16_bf16 v[34:49], v[224:227], v[70:73], v[34:49]
	s_waitcnt lgkmcnt(2)
	v_mfma_f32_32x32x16_bf16 v[34:49], v[228:231], v[74:77], v[34:49]
	s_waitcnt lgkmcnt(1)
	v_mfma_f32_32x32x16_bf16 v[34:49], v[232:235], v[78:81], v[34:49]
	s_waitcnt lgkmcnt(0)
	v_mfma_f32_32x32x16_bf16 v[34:49], v[236:239], v[86:89], v[34:49]
	s_setprio 0
	s_and_saveexec_b64 s[12:13], s[8:9]
	s_cbranch_execz .LBB0_360
	v_add_u32_e32 v104, s20, v113
	v_cmp_le_i32_e32 vcc, v104, v92
	v_add_u32_e32 v117, 2, v104
	s_nop 0
	v_cndmask_b32_e32 v50, v208, v50, vcc
	v_cmp_lt_i32_e32 vcc, v104, v92
	s_nop 1
	v_cndmask_b32_e32 v51, v208, v51, vcc
	v_cmp_le_i32_e32 vcc, v117, v92
	v_add_u32_e32 v117, 3, v104
	s_nop 0
	v_cndmask_b32_e32 v52, v208, v52, vcc
	v_cmp_le_i32_e32 vcc, v117, v92
	v_add_u32_e32 v117, 8, v104
	s_nop 0
	v_cndmask_b32_e32 v53, v208, v53, vcc
	v_cmp_le_i32_e32 vcc, v117, v92
	v_add_u32_e32 v117, 9, v104
	s_nop 0
	v_cndmask_b32_e32 v54, v208, v54, vcc
	v_cmp_le_i32_e32 vcc, v117, v92
	v_add_u32_e32 v117, 10, v104
	s_nop 0
	v_cndmask_b32_e32 v55, v208, v55, vcc
	v_cmp_le_i32_e32 vcc, v117, v92
	v_add_u32_e32 v117, 11, v104
	s_nop 0
	v_cndmask_b32_e32 v56, v208, v56, vcc
	v_cmp_le_i32_e32 vcc, v117, v92
	v_add_u32_e32 v117, 16, v104
	s_nop 0
	v_cndmask_b32_e32 v57, v208, v57, vcc
	v_cmp_le_i32_e32 vcc, v117, v92
	v_add_u32_e32 v117, 17, v104
	s_nop 0
	v_cndmask_b32_e32 v58, v208, v58, vcc
	v_cmp_le_i32_e32 vcc, v117, v92
	v_add_u32_e32 v117, 18, v104
	s_nop 0
	v_cndmask_b32_e32 v59, v208, v59, vcc
	v_cmp_le_i32_e32 vcc, v117, v92
	v_add_u32_e32 v117, 19, v104
	s_nop 0
	v_cndmask_b32_e32 v60, v208, v60, vcc
	v_cmp_le_i32_e32 vcc, v117, v92
	v_add_u32_e32 v117, 24, v104
	s_nop 0
	v_cndmask_b32_e32 v61, v208, v61, vcc
	v_cmp_le_i32_e32 vcc, v117, v92
	v_add_u32_e32 v117, 25, v104
	s_nop 0
	v_cndmask_b32_e32 v62, v208, v62, vcc
	v_cmp_le_i32_e32 vcc, v117, v92
	v_add_u32_e32 v117, 26, v104
	s_nop 0
	v_cndmask_b32_e32 v63, v208, v63, vcc
	v_cmp_le_i32_e32 vcc, v117, v92
	v_add_u32_e32 v117, 27, v104
	s_nop 0
	v_cndmask_b32_e32 v64, v208, v64, vcc
	v_cmp_le_i32_e32 vcc, v117, v92
	v_add_u32_e32 v117, 32, v104
	s_nop 0
	v_cndmask_b32_e32 v65, v208, v65, vcc
	v_cmp_le_i32_e32 vcc, v117, v92
	v_add_u32_e32 v117, 33, v104
	s_nop 0
	v_cndmask_b32_e32 v34, v208, v34, vcc
	v_cmp_le_i32_e32 vcc, v117, v92
	v_add_u32_e32 v117, 34, v104
	s_nop 0
	v_cndmask_b32_e32 v35, v208, v35, vcc
	v_cmp_le_i32_e32 vcc, v117, v92
	v_add_u32_e32 v117, 35, v104
	s_nop 0
	v_cndmask_b32_e32 v36, v208, v36, vcc
	v_cmp_le_i32_e32 vcc, v117, v92
	v_add_u32_e32 v117, 40, v104
	s_nop 0
	v_cndmask_b32_e32 v37, v208, v37, vcc
	v_cmp_le_i32_e32 vcc, v117, v92
	v_add_u32_e32 v117, 41, v104
	s_nop 0
	v_cndmask_b32_e32 v38, v208, v38, vcc
	v_cmp_le_i32_e32 vcc, v117, v92
	v_add_u32_e32 v117, 42, v104
	s_nop 0
	v_cndmask_b32_e32 v39, v208, v39, vcc
	v_cmp_le_i32_e32 vcc, v117, v92
	v_add_u32_e32 v117, 43, v104
	s_nop 0
	v_cndmask_b32_e32 v40, v208, v40, vcc
	v_cmp_le_i32_e32 vcc, v117, v92
	v_add_u32_e32 v117, 48, v104
	s_nop 0
	v_cndmask_b32_e32 v41, v208, v41, vcc
	v_cmp_le_i32_e32 vcc, v117, v92
	v_add_u32_e32 v117, 49, v104
	s_nop 0
	v_cndmask_b32_e32 v42, v208, v42, vcc
	v_cmp_le_i32_e32 vcc, v117, v92
	v_add_u32_e32 v117, 50, v104
	s_nop 0
	v_cndmask_b32_e32 v43, v208, v43, vcc
	v_cmp_le_i32_e32 vcc, v117, v92
	v_add_u32_e32 v117, 51, v104
	s_nop 0
	v_cndmask_b32_e32 v44, v208, v44, vcc
	v_cmp_le_i32_e32 vcc, v117, v92
	v_add_u32_e32 v117, 56, v104
	s_nop 0
	v_cndmask_b32_e32 v45, v208, v45, vcc
	v_cmp_le_i32_e32 vcc, v117, v92
	v_add_u32_e32 v117, 57, v104
	s_nop 0
	v_cndmask_b32_e32 v46, v208, v46, vcc
	v_cmp_le_i32_e32 vcc, v117, v92
	v_add_u32_e32 v117, 58, v104
	v_add_u32_e32 v104, 59, v104
	v_cndmask_b32_e32 v47, v208, v47, vcc
	v_cmp_le_i32_e32 vcc, v117, v92
	s_nop 1
	v_cndmask_b32_e32 v48, v208, v48, vcc
	v_cmp_le_i32_e32 vcc, v104, v92
	s_nop 1
	v_cndmask_b32_e32 v49, v208, v49, vcc
	s_branch .LBB0_360

; #define MFMA(a, b, c) __builtin_amdgcn_mfma_f32_32x32x16_bf16((a), (b), (c), 0, 0, 0)
; DI int crow(int i, int h) { return (i & 3) + 8 * (i >> 2) + 4 * h; }
; template <int DK, int DV, int MODE>
; DI bool fa_active(int kb, int wave_qmax, unsigned long long sel) {
;   bool active = true;
;   if (MODE != 0) active = (kb * 64 <= wave_qmax);
;   if (MODE == 2) {
;     const bool selbit = (sel >> kb) & 1ull;
;     if (__ballot(selbit) == 0ull) active = false;
;   }
;   return active;
; }
; template <int DK, int DV, int MODE>
; DI void fa_qk(f32x16 (&S)[2], const bf16x8 (&q)[DK / 16], const char* base, int lr, int lh) {
;   using C = FA<DK, DV>;
; #pragma unroll
;   for (int ks = 0; ks < 2; ++ks) {
; #pragma unroll
;     for (int kk = 0; kk < DK / 16; ++kk) {
;       const bf16x8 kf = *(const bf16x8*)(base + (ks * 32 + lr) * C::KSTR + (kk * 2 + lh) * 16);
;       if (kk == 0) {
; #pragma unroll
;         for (int i = 0; i < 16; ++i) S[ks][i] = 0.f;
;       }
;       S[ks] = MFMA(kf, q[kk], S[ks]);
;     }
;   }
; }
;   using C = FA<DK, DV>;
;   bool selbit = true;
;   bool need_mask = false;
;   if (MODE != 0) need_mask = (kb * 64 + 63 > wave_qmax - 31);
;   if (MODE == 2) selbit = (sel >> kb) & 1ull;
;   if (MODE == 3) need_mask = need_mask || (kb * 64 <= wave_qmax - 512);
;   const float c2 = scale * 1.4426950408889634f;
;   if (need_mask) {
; #pragma unroll
;     for (int ks = 0; ks < 2; ++ks)
; #pragma unroll
;       for (int i = 0; i < 16; ++i) {
;         const int key = kb * 64 + ks * 32 + crow(i, lh);
;         bool valid = key <= qpos;
;         if (MODE == 2) valid = valid && selbit;
;         if (MODE == 3) valid = valid && (qpos - key < 512);
;         S[ks][i] = valid ? S[ks][i] : -1e30f;
;       }
.LBB0_436:
	v_lshrrev_b64 v[66:67], s0, v[98:99]
	s_sub_i32 s8, s7, 63
	v_and_b32_e32 v66, 1, v66
	s_cmp_le_u32 s8, s20
	v_cmp_ne_u32_e32 vcc, 0, v66
	s_cselect_b64 s[8:9], -1, 0
	s_cmp_lg_u64 vcc, 0
	s_cselect_b64 s[10:11], -1, 0
	s_and_b64 s[8:9], s[10:11], s[8:9]
	s_andn2_b64 vcc, exec, s[8:9]
	v_cmp_eq_u32_e64 s[10:11], 1, v66
	s_cbranch_vccnz .LBB0_425
	s_add_i32 s6, s6, 0
	v_add3_u32 v110, s6, v115, v114
	ds_read_b128 v[216:219], v110
	ds_read_b128 v[220:223], v110 offset:32
	ds_read_b128 v[224:227], v110 offset:64
	ds_read_b128 v[228:231], v110 offset:96
	ds_read_b128 v[232:235], v110 offset:4608
	ds_read_b128 v[236:239], v110 offset:4640
	ds_read_b128 v[240:243], v110 offset:4672
	ds_read_b128 v[244:247], v110 offset:4704
	s_cmp_gt_u32 s7, s35
	s_cselect_b64 s[8:9], -1, 0
	s_cmp_le_u32 s7, s35
	s_setprio 1
	s_waitcnt lgkmcnt(7)
	v_mfma_f32_32x32x16_bf16 v[82:97], v[216:219], v[138:141], 0
	s_waitcnt lgkmcnt(6)
	v_mfma_f32_32x32x16_bf16 v[82:97], v[220:223], v[130:133], v[82:97]
	s_waitcnt lgkmcnt(5)
	v_mfma_f32_32x32x16_bf16 v[82:97], v[224:227], v[134:137], v[82:97]
	s_waitcnt lgkmcnt(4)
	v_mfma_f32_32x32x16_bf16 v[82:97], v[228:231], v[142:145], v[82:97]
	s_waitcnt lgkmcnt(3)
	v_mfma_f32_32x32x16_bf16 v[66:81], v[232:235], v[138:141], 0
	s_waitcnt lgkmcnt(2)
	v_mfma_f32_32x32x16_bf16 v[66:81], v[236:239], v[130:133], v[66:81]
	s_waitcnt lgkmcnt(1)
	v_mfma_f32_32x32x16_bf16 v[66:81], v[240:243], v[134:137], v[66:81]
	s_waitcnt lgkmcnt(0)
	v_mfma_f32_32x32x16_bf16 v[66:81], v[244:247], v[142:145], v[66:81]
	s_setprio 0
	v_add3_u32 v247, s6, v117, v115
	v_add_u32_e32 v243, 0x2000, v247
	v_add_u32_e32 v247, 0x3000, v247
	s_cbranch_scc1 .LBB0_439
	v_add_u32_e32 v110, s7, v116
	v_subrev_u32_e32 v119, 63, v110
	v_cmp_le_i32_e32 vcc, v119, v148
	s_and_b64 vcc, vcc, s[10:11]
	s_nop 0
	v_cndmask_b32_e32 v82, v208, v82, vcc
	v_cmp_lt_i32_e32 vcc, v119, v148
	s_and_b64 vcc, vcc, s[10:11]
	v_subrev_u32_e32 v119, 61, v110
	v_cndmask_b32_e32 v83, v208, v83, vcc
	v_cmp_le_i32_e32 vcc, v119, v148
	s_and_b64 vcc, vcc, s[10:11]
	v_subrev_u32_e32 v119, 60, v110
	v_cndmask_b32_e32 v84, v208, v84, vcc
	v_cmp_le_i32_e32 vcc, v119, v148
	s_and_b64 vcc, vcc, s[10:11]
	v_subrev_u32_e32 v119, 55, v110
	v_cndmask_b32_e32 v85, v208, v85, vcc
	v_cmp_le_i32_e32 vcc, v119, v148
	s_and_b64 vcc, vcc, s[10:11]
	v_subrev_u32_e32 v119, 54, v110
	v_cndmask_b32_e32 v86, v208, v86, vcc
	v_cmp_le_i32_e32 vcc, v119, v148
	s_and_b64 vcc, vcc, s[10:11]
	v_subrev_u32_e32 v119, 53, v110
	v_cndmask_b32_e32 v87, v208, v87, vcc
	v_cmp_le_i32_e32 vcc, v119, v148
	s_and_b64 vcc, vcc, s[10:11]
	v_subrev_u32_e32 v119, 52, v110
	v_cndmask_b32_e32 v88, v208, v88, vcc
	v_cmp_le_i32_e32 vcc, v119, v148
	s_and_b64 vcc, vcc, s[10:11]
	v_subrev_u32_e32 v119, 47, v110
	v_cndmask_b32_e32 v89, v208, v89, vcc
	v_cmp_le_i32_e32 vcc, v119, v148
	s_and_b64 vcc, vcc, s[10:11]
	v_subrev_u32_e32 v119, 46, v110
	v_cndmask_b32_e32 v90, v208, v90, vcc
	v_cmp_le_i32_e32 vcc, v119, v148
	s_and_b64 vcc, vcc, s[10:11]
	v_subrev_u32_e32 v119, 45, v110
	v_cndmask_b32_e32 v91, v208, v91, vcc
	v_cmp_le_i32_e32 vcc, v119, v148
	s_and_b64 vcc, vcc, s[10:11]
	v_subrev_u32_e32 v119, 44, v110
	v_cndmask_b32_e32 v92, v208, v92, vcc
	v_cmp_le_i32_e32 vcc, v119, v148
	s_and_b64 vcc, vcc, s[10:11]
	v_subrev_u32_e32 v119, 39, v110
	v_cndmask_b32_e32 v93, v208, v93, vcc
	v_cmp_le_i32_e32 vcc, v119, v148
	s_and_b64 vcc, vcc, s[10:11]
	v_subrev_u32_e32 v119, 38, v110
	v_cndmask_b32_e32 v94, v208, v94, vcc
	v_cmp_le_i32_e32 vcc, v119, v148
	s_and_b64 vcc, vcc, s[10:11]
	v_subrev_u32_e32 v119, 37, v110
	v_cndmask_b32_e32 v95, v208, v95, vcc
	v_cmp_le_i32_e32 vcc, v119, v148
	s_and_b64 vcc, vcc, s[10:11]
	v_subrev_u32_e32 v119, 36, v110
	v_cndmask_b32_e32 v96, v208, v96, vcc
	v_cmp_le_i32_e32 vcc, v119, v148
	s_and_b64 vcc, vcc, s[10:11]
	v_subrev_u32_e32 v119, 31, v110
	v_cndmask_b32_e32 v97, v208, v97, vcc
	v_cmp_le_i32_e32 vcc, v119, v148
	s_and_b64 vcc, vcc, s[10:11]
	v_subrev_u32_e32 v119, 30, v110
	v_cndmask_b32_e32 v66, v208, v66, vcc
	v_cmp_le_i32_e32 vcc, v119, v148
	s_and_b64 vcc, vcc, s[10:11]
	v_subrev_u32_e32 v119, 29, v110
	v_cndmask_b32_e32 v67, v208, v67, vcc
	v_cmp_le_i32_e32 vcc, v119, v148
	s_and_b64 vcc, vcc, s[10:11]
	v_subrev_u32_e32 v119, 28, v110
	v_cndmask_b32_e32 v68, v208, v68, vcc
	v_cmp_le_i32_e32 vcc, v119, v148
	s_and_b64 vcc, vcc, s[10:11]
	v_subrev_u32_e32 v119, 23, v110
	v_cndmask_b32_e32 v69, v208, v69, vcc
	v_cmp_le_i32_e32 vcc, v119, v148
	s_and_b64 vcc, vcc, s[10:11]
	v_subrev_u32_e32 v119, 22, v110
	v_cndmask_b32_e32 v70, v208, v70, vcc
	v_cmp_le_i32_e32 vcc, v119, v148
	s_and_b64 vcc, vcc, s[10:11]
	v_subrev_u32_e32 v119, 21, v110
	v_cndmask_b32_e32 v71, v208, v71, vcc
	v_cmp_le_i32_e32 vcc, v119, v148
	s_and_b64 vcc, vcc, s[10:11]
	v_subrev_u32_e32 v119, 20, v110
	v_cndmask_b32_e32 v72, v208, v72, vcc
	v_cmp_le_i32_e32 vcc, v119, v148
	s_and_b64 vcc, vcc, s[10:11]
	v_add_u32_e32 v119, -15, v110
	v_cndmask_b32_e32 v73, v208, v73, vcc
	v_cmp_le_i32_e32 vcc, v119, v148
	s_and_b64 vcc, vcc, s[10:11]
	v_add_u32_e32 v119, -14, v110
	v_cndmask_b32_e32 v74, v208, v74, vcc
	v_cmp_le_i32_e32 vcc, v119, v148
	s_and_b64 vcc, vcc, s[10:11]
	v_add_u32_e32 v119, -13, v110
	v_cndmask_b32_e32 v75, v208, v75, vcc
	v_cmp_le_i32_e32 vcc, v119, v148
	s_and_b64 vcc, vcc, s[10:11]
	v_add_u32_e32 v119, -12, v110
	v_cndmask_b32_e32 v76, v208, v76, vcc
	v_cmp_le_i32_e32 vcc, v119, v148
	s_and_b64 vcc, vcc, s[10:11]
	v_add_u32_e32 v119, -7, v110
	v_cndmask_b32_e32 v77, v208, v77, vcc
	v_cmp_le_i32_e32 vcc, v119, v148
	s_and_b64 vcc, vcc, s[10:11]
	v_add_u32_e32 v119, -6, v110
	v_cndmask_b32_e32 v78, v208, v78, vcc
	v_cmp_le_i32_e32 vcc, v119, v148
	s_and_b64 vcc, vcc, s[10:11]
	v_add_u32_e32 v119, -5, v110
	v_cndmask_b32_e32 v79, v208, v79, vcc
	v_cmp_le_i32_e32 vcc, v119, v148
	s_and_b64 vcc, vcc, s[10:11]
	v_add_u32_e32 v110, -4, v110
	v_cndmask_b32_e32 v80, v208, v80, vcc
	v_cmp_le_i32_e32 vcc, v110, v148
	s_and_b64 vcc, vcc, s[10:11]
	s_nop 0
	v_cndmask_b32_e32 v81, v208, v81, vcc

; #define MFMA(a, b, c) __builtin_amdgcn_mfma_f32_32x32x16_bf16((a), (b), (c), 0, 0, 0)
; template <int DK, int DV, int MODE>
; DI bool fa_active(int kb, int wave_qmax, unsigned long long sel) {
;   bool active = true;
;   if (MODE != 0) active = (kb * 64 <= wave_qmax);
;   if (MODE == 2) {
;     const bool selbit = (sel >> kb) & 1ull;
;     if (__ballot(selbit) == 0ull) active = false;
;   }
;   return active;
; }
; template <int DK, int DV, int MODE>
; DI void fa_qk(f32x16 (&S)[2], const bf16x8 (&q)[DK / 16], const char* base, int lr, int lh) {
;   using C = FA<DK, DV>;
; #pragma unroll
;   for (int ks = 0; ks < 2; ++ks) {
; #pragma unroll
;     for (int kk = 0; kk < DK / 16; ++kk) {
;       const bf16x8 kf = *(const bf16x8*)(base + (ks * 32 + lr) * C::KSTR + (kk * 2 + lh) * 16);
;       if (kk == 0) {
; #pragma unroll
;         for (int i = 0; i < 16; ++i) S[ks][i] = 0.f;
;       }
;       S[ks] = MFMA(kf, q[kk], S[ks]);
;     }
;   }
; }
.LBB0_467:
	s_add_i32 s6, s38, s17
	s_add_i32 s1, s6, 0xdc0
	s_cmp_gt_u32 s1, s20
	s_cbranch_scc1 .LBB0_456
	s_add_i32 s0, s0, 0
	v_add3_u32 v162, s0, v174, v173
	ds_read_b128 v[216:219], v162
	ds_read_b128 v[220:223], v162 offset:32
	ds_read_b128 v[224:227], v162 offset:64
	ds_read_b128 v[228:231], v162 offset:96
	ds_read_b128 v[232:235], v162 offset:4608
	ds_read_b128 v[236:239], v162 offset:4640
	ds_read_b128 v[240:243], v162 offset:4672
	ds_read_b128 v[244:247], v162 offset:4704
	s_addk_i32 s6, 0xddf
	s_cmp_gt_u32 s6, s45
	s_cselect_b64 s[8:9], -1, 0
	s_cmp_le_i32 s1, s16
	s_cselect_b64 s[10:11], -1, 0
	s_or_b64 s[8:9], s[8:9], s[10:11]
	s_andn2_b64 vcc, exec, s[8:9]
	s_setprio 1
	s_waitcnt lgkmcnt(7)
	v_mfma_f32_32x32x16_bf16 v[114:129], v[216:219], v[138:141], 0
	s_waitcnt lgkmcnt(6)
	v_mfma_f32_32x32x16_bf16 v[114:129], v[220:223], v[130:133], v[114:129]
	s_waitcnt lgkmcnt(5)
	v_mfma_f32_32x32x16_bf16 v[114:129], v[224:227], v[134:137], v[114:129]
	s_waitcnt lgkmcnt(4)
	v_mfma_f32_32x32x16_bf16 v[114:129], v[228:231], v[142:145], v[114:129]
	s_waitcnt lgkmcnt(3)
	v_mfma_f32_32x32x16_bf16 v[98:113], v[232:235], v[138:141], 0
	s_waitcnt lgkmcnt(2)
	v_mfma_f32_32x32x16_bf16 v[98:113], v[236:239], v[130:133], v[98:113]
	s_waitcnt lgkmcnt(1)
	v_mfma_f32_32x32x16_bf16 v[98:113], v[240:243], v[134:137], v[98:113]
	s_waitcnt lgkmcnt(0)
	v_mfma_f32_32x32x16_bf16 v[98:113], v[244:247], v[142:145], v[98:113]
	s_setprio 0
	v_add3_u32 v247, s0, v176, v174
	v_add_u32_e32 v243, 0x2000, v247
	v_add_u32_e32 v247, 0x3000, v247
	s_cbranch_vccnz .LBB0_470
; DI int crow(int i, int h) { return (i & 3) + 8 * (i >> 2) + 4 * h; }
;     ...
;   if (need_mask) {
; #pragma unroll
;     for (int ks = 0; ks < 2; ++ks)
; #pragma unroll
;       for (int i = 0; i < 16; ++i) {
;         const int key = kb * 64 + ks * 32 + crow(i, lh);
;         bool valid = key <= qpos;
;         if (MODE == 2) valid = valid && selbit;
;         if (MODE == 3) valid = valid && (qpos - key < 512);
;         S[ks][i] = valid ? S[ks][i] : -1e30f;
;       }
	v_add_u32_e32 v162, s17, v177
	v_add_u32_e32 v179, 0xdc0, v162
	v_cmp_le_i32_e32 vcc, v179, v148
	v_cmp_gt_i32_e64 s[10:11], v179, v175
	s_and_b64 vcc, vcc, s[10:11]
	v_cndmask_b32_e32 v114, v208, v114, vcc
	v_cmp_lt_i32_e32 vcc, v179, v148
	v_cmp_ge_i32_e64 s[10:11], v179, v175
	s_and_b64 vcc, vcc, s[10:11]
	v_add_u32_e32 v179, 0xdc2, v162
	v_cndmask_b32_e32 v115, v208, v115, vcc
	v_cmp_le_i32_e32 vcc, v179, v148
	v_cmp_gt_i32_e64 s[10:11], v179, v175
	s_and_b64 vcc, vcc, s[10:11]
	v_add_u32_e32 v179, 0xdc3, v162
	v_cndmask_b32_e32 v116, v208, v116, vcc
	v_cmp_le_i32_e32 vcc, v179, v148
	v_cmp_gt_i32_e64 s[10:11], v179, v175
	s_and_b64 vcc, vcc, s[10:11]
	v_add_u32_e32 v179, 0xdc8, v162
	v_cndmask_b32_e32 v117, v208, v117, vcc
	v_cmp_le_i32_e32 vcc, v179, v148
	v_cmp_gt_i32_e64 s[10:11], v179, v175
	s_and_b64 vcc, vcc, s[10:11]
	v_add_u32_e32 v179, 0xdc9, v162
	v_cndmask_b32_e32 v118, v208, v118, vcc
	v_cmp_le_i32_e32 vcc, v179, v148
	v_cmp_gt_i32_e64 s[10:11], v179, v175
	s_and_b64 vcc, vcc, s[10:11]
	v_add_u32_e32 v179, 0xdca, v162
	v_cndmask_b32_e32 v119, v208, v119, vcc
	v_cmp_le_i32_e32 vcc, v179, v148
	v_cmp_gt_i32_e64 s[10:11], v179, v175
	s_and_b64 vcc, vcc, s[10:11]
	v_add_u32_e32 v179, 0xdcb, v162
	v_cndmask_b32_e32 v120, v208, v120, vcc
	v_cmp_le_i32_e32 vcc, v179, v148
	v_cmp_gt_i32_e64 s[10:11], v179, v175
	s_and_b64 vcc, vcc, s[10:11]
	v_add_u32_e32 v179, 0xdd0, v162
	v_cndmask_b32_e32 v121, v208, v121, vcc
	v_cmp_le_i32_e32 vcc, v179, v148
	v_cmp_gt_i32_e64 s[10:11], v179, v175
	s_and_b64 vcc, vcc, s[10:11]
	v_add_u32_e32 v179, 0xdd1, v162
	v_cndmask_b32_e32 v122, v208, v122, vcc
	v_cmp_le_i32_e32 vcc, v179, v148
	v_cmp_gt_i32_e64 s[10:11], v179, v175
	s_and_b64 vcc, vcc, s[10:11]
	v_add_u32_e32 v179, 0xdd2, v162
	v_cndmask_b32_e32 v123, v208, v123, vcc
	v_cmp_le_i32_e32 vcc, v179, v148
	v_cmp_gt_i32_e64 s[10:11], v179, v175
	s_and_b64 vcc, vcc, s[10:11]
	v_add_u32_e32 v179, 0xdd3, v162
	v_cndmask_b32_e32 v124, v208, v124, vcc
	v_cmp_le_i32_e32 vcc, v179, v148
	v_cmp_gt_i32_e64 s[10:11], v179, v175
	s_and_b64 vcc, vcc, s[10:11]
	v_add_u32_e32 v179, 0xdd8, v162
	v_cndmask_b32_e32 v125, v208, v125, vcc
	v_cmp_le_i32_e32 vcc, v179, v148
	v_cmp_gt_i32_e64 s[10:11], v179, v175
	s_and_b64 vcc, vcc, s[10:11]
	v_add_u32_e32 v179, 0xdd9, v162
	v_cndmask_b32_e32 v126, v208, v126, vcc
	v_cmp_le_i32_e32 vcc, v179, v148
	v_cmp_gt_i32_e64 s[10:11], v179, v175
	s_and_b64 vcc, vcc, s[10:11]
	v_add_u32_e32 v179, 0xdda, v162
	v_cndmask_b32_e32 v127, v208, v127, vcc
	v_cmp_le_i32_e32 vcc, v179, v148
	v_cmp_gt_i32_e64 s[10:11], v179, v175
	s_and_b64 vcc, vcc, s[10:11]
	v_add_u32_e32 v179, 0xddb, v162
	v_cndmask_b32_e32 v128, v208, v128, vcc
	v_cmp_le_i32_e32 vcc, v179, v148
	v_cmp_gt_i32_e64 s[10:11], v179, v175
	s_and_b64 vcc, vcc, s[10:11]
	v_add_u32_e32 v179, 0xde0, v162
	v_cndmask_b32_e32 v129, v208, v129, vcc
	v_cmp_le_i32_e32 vcc, v179, v148
	v_cmp_gt_i32_e64 s[10:11], v179, v175
	s_and_b64 vcc, vcc, s[10:11]
	v_add_u32_e32 v179, 0xde1, v162
	v_cndmask_b32_e32 v98, v208, v98, vcc
	v_cmp_le_i32_e32 vcc, v179, v148
	v_cmp_gt_i32_e64 s[10:11], v179, v175
	s_and_b64 vcc, vcc, s[10:11]
	v_add_u32_e32 v179, 0xde2, v162
	v_cndmask_b32_e32 v99, v208, v99, vcc
	v_cmp_le_i32_e32 vcc, v179, v148
	v_cmp_gt_i32_e64 s[10:11], v179, v175
	s_and_b64 vcc, vcc, s[10:11]
	v_add_u32_e32 v179, 0xde3, v162
	v_cndmask_b32_e32 v100, v208, v100, vcc
	v_cmp_le_i32_e32 vcc, v179, v148
	v_cmp_gt_i32_e64 s[10:11], v179, v175
	s_and_b64 vcc, vcc, s[10:11]
	v_add_u32_e32 v179, 0xde8, v162
	v_cndmask_b32_e32 v101, v208, v101, vcc
	v_cmp_le_i32_e32 vcc, v179, v148
	v_cmp_gt_i32_e64 s[10:11], v179, v175
	s_and_b64 vcc, vcc, s[10:11]
	v_add_u32_e32 v179, 0xde9, v162
	v_cndmask_b32_e32 v102, v208, v102, vcc
	v_cmp_le_i32_e32 vcc, v179, v148
	v_cmp_gt_i32_e64 s[10:11], v179, v175
	s_and_b64 vcc, vcc, s[10:11]
	v_add_u32_e32 v179, 0xdea, v162
	v_cndmask_b32_e32 v103, v208, v103, vcc
	v_cmp_le_i32_e32 vcc, v179, v148
	v_cmp_gt_i32_e64 s[10:11], v179, v175
	s_and_b64 vcc, vcc, s[10:11]
	v_add_u32_e32 v179, 0xdeb, v162
	v_cndmask_b32_e32 v104, v208, v104, vcc
	v_cmp_le_i32_e32 vcc, v179, v148
	v_cmp_gt_i32_e64 s[10:11], v179, v175
	s_and_b64 vcc, vcc, s[10:11]
	v_add_u32_e32 v179, 0xdf0, v162
	v_cndmask_b32_e32 v105, v208, v105, vcc
	v_cmp_le_i32_e32 vcc, v179, v148
	v_cmp_gt_i32_e64 s[10:11], v179, v175
	s_and_b64 vcc, vcc, s[10:11]
	v_add_u32_e32 v179, 0xdf1, v162
	v_cndmask_b32_e32 v106, v208, v106, vcc
	v_cmp_le_i32_e32 vcc, v179, v148
	v_cmp_gt_i32_e64 s[10:11], v179, v175
	s_and_b64 vcc, vcc, s[10:11]
	v_add_u32_e32 v179, 0xdf2, v162
	v_cndmask_b32_e32 v107, v208, v107, vcc
	v_cmp_le_i32_e32 vcc, v179, v148
	v_cmp_gt_i32_e64 s[10:11], v179, v175
	s_and_b64 vcc, vcc, s[10:11]
	v_add_u32_e32 v179, 0xdf3, v162
	v_cndmask_b32_e32 v108, v208, v108, vcc
	v_cmp_le_i32_e32 vcc, v179, v148
	v_cmp_gt_i32_e64 s[10:11], v179, v175
	s_and_b64 vcc, vcc, s[10:11]
	v_add_u32_e32 v179, 0xdf8, v162
	v_cndmask_b32_e32 v109, v208, v109, vcc
	v_cmp_le_i32_e32 vcc, v179, v148
	v_cmp_gt_i32_e64 s[10:11], v179, v175
	s_and_b64 vcc, vcc, s[10:11]
	v_add_u32_e32 v179, 0xdf9, v162
	v_cndmask_b32_e32 v110, v208, v110, vcc
	v_cmp_le_i32_e32 vcc, v179, v148
	v_cmp_gt_i32_e64 s[10:11], v179, v175
	s_and_b64 vcc, vcc, s[10:11]
	v_add_u32_e32 v179, 0xdfa, v162
	v_cndmask_b32_e32 v111, v208, v111, vcc
	v_cmp_le_i32_e32 vcc, v179, v148
	v_cmp_gt_i32_e64 s[10:11], v179, v175
	s_and_b64 vcc, vcc, s[10:11]
	v_add_u32_e32 v162, 0xdfb, v162
	v_cndmask_b32_e32 v112, v208, v112, vcc
	v_cmp_le_i32_e32 vcc, v162, v148
	v_cmp_gt_i32_e64 s[10:11], v162, v175
	s_and_b64 vcc, vcc, s[10:11]
	v_cndmask_b32_e32 v113, v208, v113, vcc

; #define MFMA(a, b, c) __builtin_amdgcn_mfma_f32_32x32x16_bf16((a), (b), (c), 0, 0, 0)
; DI int crow(int i, int h) { return (i & 3) + 8 * (i >> 2) + 4 * h; }
; template <int DK, int DV, int MODE>
; DI void fa_qk(f32x16 (&S)[2], const bf16x8 (&q)[DK / 16], const char* base, int lr, int lh) {
;   using C = FA<DK, DV>;
; #pragma unroll
;   for (int ks = 0; ks < 2; ++ks) {
; #pragma unroll
;     for (int kk = 0; kk < DK / 16; ++kk) {
;       const bf16x8 kf = *(const bf16x8*)(base + (ks * 32 + lr) * C::KSTR + (kk * 2 + lh) * 16);
;       if (kk == 0) {
; #pragma unroll
;         for (int i = 0; i < 16; ++i) S[ks][i] = 0.f;
;       }
;       S[ks] = MFMA(kf, q[kk], S[ks]);
;     }
;   }
; }
;   using C = FA<DK, DV>;
;   bool selbit = true;
;   bool need_mask = false;
;   if (MODE != 0) need_mask = (kb * 64 + 63 > wave_qmax - 31);
;   if (MODE == 2) selbit = (sel >> kb) & 1ull;
;   if (MODE == 3) need_mask = need_mask || (kb * 64 <= wave_qmax - 512);
;   const float c2 = scale * 1.4426950408889634f;
;   if (need_mask) {
; #pragma unroll
;     for (int ks = 0; ks < 2; ++ks)
; #pragma unroll
;       for (int i = 0; i < 16; ++i) {
;         const int key = kb * 64 + ks * 32 + crow(i, lh);
;         bool valid = key <= qpos;
;         if (MODE == 2) valid = valid && selbit;
;         if (MODE == 3) valid = valid && (qpos - key < 512);
;         S[ks][i] = valid ? S[ks][i] : -1e30f;
;       }
.LBB0_499:
	v_cmp_le_i32_e32 vcc, s21, v110
	s_and_saveexec_b64 s[10:11], vcc
	s_cbranch_execz .LBB0_488
	s_add_i32 s6, s6, 0
	v_add3_u32 v104, s6, v112, v111
	ds_read_b128 v[34:37], v104
	ds_read_b128 v[38:41], v104 offset:32
	ds_read_b128 v[42:45], v104 offset:64
	ds_read_b128 v[46:49], v104 offset:96
	ds_read_b128 v[118:121], v104 offset:128
	ds_read_b128 v[122:125], v104 offset:160
	ds_read_b128 v[216:219], v104 offset:6656
	ds_read_b128 v[220:223], v104 offset:6688
	ds_read_b128 v[224:227], v104 offset:6720
	ds_read_b128 v[228:231], v104 offset:6752
	ds_read_b128 v[232:235], v104 offset:6784
	ds_read_b128 v[236:239], v104 offset:6816
	s_add_i32 s7, s21, 63
	v_cmp_gt_i32_e64 s[8:9], s7, v106
	v_add3_u32 v130, s6, v114, v115
	v_add_u32_e32 v131, 0x3000, v130
	v_add_u32_e32 v130, 0x4000, v130
	s_setprio 1
	s_waitcnt lgkmcnt(11)
	v_mfma_f32_32x32x16_bf16 v[50:65], v[34:37], v[82:85], 0
	s_waitcnt lgkmcnt(10)
	v_mfma_f32_32x32x16_bf16 v[50:65], v[38:41], v[66:69], v[50:65]
	s_waitcnt lgkmcnt(9)
	v_mfma_f32_32x32x16_bf16 v[50:65], v[42:45], v[70:73], v[50:65]
	s_waitcnt lgkmcnt(8)
	v_mfma_f32_32x32x16_bf16 v[50:65], v[46:49], v[74:77], v[50:65]
	s_waitcnt lgkmcnt(7)
	v_mfma_f32_32x32x16_bf16 v[50:65], v[118:121], v[78:81], v[50:65]
	s_waitcnt lgkmcnt(6)
	v_mfma_f32_32x32x16_bf16 v[50:65], v[122:125], v[86:89], v[50:65]
	s_waitcnt lgkmcnt(5)
	v_mfma_f32_32x32x16_bf16 v[34:49], v[216:219], v[82:85], 0
	s_waitcnt lgkmcnt(4)
	v_mfma_f32_32x32x16_bf16 v[34:49], v[220:223], v[66:69], v[34:49]
	s_waitcnt lgkmcnt(3)
	v_mfma_f32_32x32x16_bf16 v[34:49], v[224:227], v[70:73], v[34:49]
	s_waitcnt lgkmcnt(2)
	v_mfma_f32_32x32x16_bf16 v[34:49], v[228:231], v[74:77], v[34:49]
	s_waitcnt lgkmcnt(1)
	v_mfma_f32_32x32x16_bf16 v[34:49], v[232:235], v[78:81], v[34:49]
	s_waitcnt lgkmcnt(0)
	v_mfma_f32_32x32x16_bf16 v[34:49], v[236:239], v[86:89], v[34:49]
	s_setprio 0
	s_and_saveexec_b64 s[12:13], s[8:9]
	s_cbranch_execz .LBB0_485
	v_add_u32_e32 v104, s21, v113
	v_cmp_le_i32_e32 vcc, v104, v92
	v_add_u32_e32 v117, 2, v104
	s_nop 0
	v_cndmask_b32_e32 v50, v208, v50, vcc
	v_cmp_lt_i32_e32 vcc, v104, v92
	s_nop 1
	v_cndmask_b32_e32 v51, v208, v51, vcc
	v_cmp_le_i32_e32 vcc, v117, v92
	v_add_u32_e32 v117, 3, v104
	s_nop 0
	v_cndmask_b32_e32 v52, v208, v52, vcc
	v_cmp_le_i32_e32 vcc, v117, v92
	v_add_u32_e32 v117, 8, v104
	s_nop 0
	v_cndmask_b32_e32 v53, v208, v53, vcc
	v_cmp_le_i32_e32 vcc, v117, v92
	v_add_u32_e32 v117, 9, v104
	s_nop 0
	v_cndmask_b32_e32 v54, v208, v54, vcc
	v_cmp_le_i32_e32 vcc, v117, v92
	v_add_u32_e32 v117, 10, v104
	s_nop 0
	v_cndmask_b32_e32 v55, v208, v55, vcc
	v_cmp_le_i32_e32 vcc, v117, v92
	v_add_u32_e32 v117, 11, v104
	s_nop 0
	v_cndmask_b32_e32 v56, v208, v56, vcc
	v_cmp_le_i32_e32 vcc, v117, v92
	v_add_u32_e32 v117, 16, v104
	s_nop 0
	v_cndmask_b32_e32 v57, v208, v57, vcc
	v_cmp_le_i32_e32 vcc, v117, v92
	v_add_u32_e32 v117, 17, v104
	s_nop 0
	v_cndmask_b32_e32 v58, v208, v58, vcc
	v_cmp_le_i32_e32 vcc, v117, v92
	v_add_u32_e32 v117, 18, v104
	s_nop 0
	v_cndmask_b32_e32 v59, v208, v59, vcc
	v_cmp_le_i32_e32 vcc, v117, v92
	v_add_u32_e32 v117, 19, v104
	s_nop 0
	v_cndmask_b32_e32 v60, v208, v60, vcc
	v_cmp_le_i32_e32 vcc, v117, v92
	v_add_u32_e32 v117, 24, v104
	s_nop 0
	v_cndmask_b32_e32 v61, v208, v61, vcc
	v_cmp_le_i32_e32 vcc, v117, v92
	v_add_u32_e32 v117, 25, v104
	s_nop 0
	v_cndmask_b32_e32 v62, v208, v62, vcc
	v_cmp_le_i32_e32 vcc, v117, v92
	v_add_u32_e32 v117, 26, v104
	s_nop 0
	v_cndmask_b32_e32 v63, v208, v63, vcc
	v_cmp_le_i32_e32 vcc, v117, v92
	v_add_u32_e32 v117, 27, v104
	s_nop 0
	v_cndmask_b32_e32 v64, v208, v64, vcc
	v_cmp_le_i32_e32 vcc, v117, v92
	v_add_u32_e32 v117, 32, v104
	s_nop 0
	v_cndmask_b32_e32 v65, v208, v65, vcc
	v_cmp_le_i32_e32 vcc, v117, v92
	v_add_u32_e32 v117, 33, v104
	s_nop 0
	v_cndmask_b32_e32 v34, v208, v34, vcc
	v_cmp_le_i32_e32 vcc, v117, v92
	v_add_u32_e32 v117, 34, v104
	s_nop 0
	v_cndmask_b32_e32 v35, v208, v35, vcc
	v_cmp_le_i32_e32 vcc, v117, v92
	v_add_u32_e32 v117, 35, v104
	s_nop 0
	v_cndmask_b32_e32 v36, v208, v36, vcc
	v_cmp_le_i32_e32 vcc, v117, v92
	v_add_u32_e32 v117, 40, v104
	s_nop 0
	v_cndmask_b32_e32 v37, v208, v37, vcc
	v_cmp_le_i32_e32 vcc, v117, v92
	v_add_u32_e32 v117, 41, v104
	s_nop 0
	v_cndmask_b32_e32 v38, v208, v38, vcc
	v_cmp_le_i32_e32 vcc, v117, v92
	v_add_u32_e32 v117, 42, v104
	s_nop 0
	v_cndmask_b32_e32 v39, v208, v39, vcc
	v_cmp_le_i32_e32 vcc, v117, v92
	v_add_u32_e32 v117, 43, v104
	s_nop 0
	v_cndmask_b32_e32 v40, v208, v40, vcc
	v_cmp_le_i32_e32 vcc, v117, v92
	v_add_u32_e32 v117, 48, v104
	s_nop 0
	v_cndmask_b32_e32 v41, v208, v41, vcc
	v_cmp_le_i32_e32 vcc, v117, v92
	v_add_u32_e32 v117, 49, v104
	s_nop 0
	v_cndmask_b32_e32 v42, v208, v42, vcc
	v_cmp_le_i32_e32 vcc, v117, v92
	v_add_u32_e32 v117, 50, v104
	s_nop 0
	v_cndmask_b32_e32 v43, v208, v43, vcc
	v_cmp_le_i32_e32 vcc, v117, v92
	v_add_u32_e32 v117, 51, v104
	s_nop 0
	v_cndmask_b32_e32 v44, v208, v44, vcc
	v_cmp_le_i32_e32 vcc, v117, v92
	v_add_u32_e32 v117, 56, v104
	s_nop 0
	v_cndmask_b32_e32 v45, v208, v45, vcc
	v_cmp_le_i32_e32 vcc, v117, v92
	v_add_u32_e32 v117, 57, v104
	s_nop 0
	v_cndmask_b32_e32 v46, v208, v46, vcc
	v_cmp_le_i32_e32 vcc, v117, v92
	v_add_u32_e32 v117, 58, v104
	v_add_u32_e32 v104, 59, v104
	v_cndmask_b32_e32 v47, v208, v47, vcc
	v_cmp_le_i32_e32 vcc, v117, v92
	s_nop 1
	v_cndmask_b32_e32 v48, v208, v48, vcc
	v_cmp_le_i32_e32 vcc, v104, v92
	s_nop 1
	v_cndmask_b32_e32 v49, v208, v49, vcc
	s_branch .LBB0_485

; #define MFMA(a, b, c) __builtin_amdgcn_mfma_f32_32x32x16_bf16((a), (b), (c), 0, 0, 0)
; DI int crow(int i, int h) { return (i & 3) + 8 * (i >> 2) + 4 * h; }
; template <int DK, int DV, int MODE>
; DI bool fa_active(int kb, int wave_qmax, unsigned long long sel) {
;   bool active = true;
;   if (MODE != 0) active = (kb * 64 <= wave_qmax);
;   if (MODE == 2) {
;     const bool selbit = (sel >> kb) & 1ull;
;     if (__ballot(selbit) == 0ull) active = false;
;   }
;   return active;
; }
; template <int DK, int DV, int MODE>
; DI void fa_qk(f32x16 (&S)[2], const bf16x8 (&q)[DK / 16], const char* base, int lr, int lh) {
;   using C = FA<DK, DV>;
; #pragma unroll
;   for (int ks = 0; ks < 2; ++ks) {
; #pragma unroll
;     for (int kk = 0; kk < DK / 16; ++kk) {
;       const bf16x8 kf = *(const bf16x8*)(base + (ks * 32 + lr) * C::KSTR + (kk * 2 + lh) * 16);
;       if (kk == 0) {
; #pragma unroll
;         for (int i = 0; i < 16; ++i) S[ks][i] = 0.f;
;       }
;       S[ks] = MFMA(kf, q[kk], S[ks]);
;     }
;   }
; }
;   using C = FA<DK, DV>;
;   bool selbit = true;
;   bool need_mask = false;
;   if (MODE != 0) need_mask = (kb * 64 + 63 > wave_qmax - 31);
;   if (MODE == 2) selbit = (sel >> kb) & 1ull;
;   if (MODE == 3) need_mask = need_mask || (kb * 64 <= wave_qmax - 512);
;   const float c2 = scale * 1.4426950408889634f;
;   if (need_mask) {
; #pragma unroll
;     for (int ks = 0; ks < 2; ++ks)
; #pragma unroll
;       for (int i = 0; i < 16; ++i) {
;         const int key = kb * 64 + ks * 32 + crow(i, lh);
;         bool valid = key <= qpos;
;         if (MODE == 2) valid = valid && selbit;
;         if (MODE == 3) valid = valid && (qpos - key < 512);
;         S[ks][i] = valid ? S[ks][i] : -1e30f;
;       }
.LBB0_561:
	v_lshrrev_b64 v[80:81], s0, v[2:3]
	s_sub_i32 s8, s7, 63
	v_and_b32_e32 v14, 1, v80
	s_cmp_le_u32 s8, s20
	v_cmp_ne_u32_e32 vcc, 0, v14
	s_cselect_b64 s[8:9], -1, 0
	s_cmp_lg_u64 vcc, 0
	s_cselect_b64 s[10:11], -1, 0
	s_and_b64 s[8:9], s[10:11], s[8:9]
	s_andn2_b64 vcc, exec, s[8:9]
	v_cmp_eq_u32_e64 s[10:11], 1, v14
	s_cbranch_vccnz .LBB0_550
	s_add_i32 s6, s6, 0
	v_add3_u32 v14, s6, v115, v114
	ds_read_b128 v[216:219], v14
	ds_read_b128 v[220:223], v14 offset:32
	ds_read_b128 v[224:227], v14 offset:64
	ds_read_b128 v[228:231], v14 offset:96
	ds_read_b128 v[232:235], v14 offset:4608
	ds_read_b128 v[236:239], v14 offset:4640
	ds_read_b128 v[240:243], v14 offset:4672
	ds_read_b128 v[244:247], v14 offset:4704
	s_cmp_gt_u32 s7, s35
	s_cselect_b64 s[8:9], -1, 0
	s_cmp_le_u32 s7, s35
	s_setprio 1
	s_waitcnt lgkmcnt(7)
	v_mfma_f32_32x32x16_bf16 v[96:111], v[216:219], v[152:155], 0
	s_waitcnt lgkmcnt(6)
	v_mfma_f32_32x32x16_bf16 v[96:111], v[220:223], v[144:147], v[96:111]
	s_waitcnt lgkmcnt(5)
	v_mfma_f32_32x32x16_bf16 v[96:111], v[224:227], v[148:151], v[96:111]
	s_waitcnt lgkmcnt(4)
	v_mfma_f32_32x32x16_bf16 v[96:111], v[228:231], v[156:159], v[96:111]
	s_waitcnt lgkmcnt(3)
	v_mfma_f32_32x32x16_bf16 v[80:95], v[232:235], v[152:155], 0
	s_waitcnt lgkmcnt(2)
	v_mfma_f32_32x32x16_bf16 v[80:95], v[236:239], v[144:147], v[80:95]
	s_waitcnt lgkmcnt(1)
	v_mfma_f32_32x32x16_bf16 v[80:95], v[240:243], v[148:151], v[80:95]
	s_waitcnt lgkmcnt(0)
	v_mfma_f32_32x32x16_bf16 v[80:95], v[244:247], v[156:159], v[80:95]
	s_setprio 0
	v_add3_u32 v247, s6, v117, v115
	v_add_u32_e32 v243, 0x2000, v247
	v_add_u32_e32 v247, 0x3000, v247
	s_cbranch_scc1 .LBB0_564
	v_add_u32_e32 v14, s7, v116
	v_subrev_u32_e32 v119, 63, v14
	v_cmp_le_i32_e32 vcc, v119, v162
	s_and_b64 vcc, vcc, s[10:11]
	s_nop 0
	v_cndmask_b32_e32 v96, v208, v96, vcc
	v_cmp_lt_i32_e32 vcc, v119, v162
	s_and_b64 vcc, vcc, s[10:11]
	v_subrev_u32_e32 v119, 61, v14
	v_cndmask_b32_e32 v97, v208, v97, vcc
	v_cmp_le_i32_e32 vcc, v119, v162
	s_and_b64 vcc, vcc, s[10:11]
	v_subrev_u32_e32 v119, 60, v14
	v_cndmask_b32_e32 v98, v208, v98, vcc
	v_cmp_le_i32_e32 vcc, v119, v162
	s_and_b64 vcc, vcc, s[10:11]
	v_subrev_u32_e32 v119, 55, v14
	v_cndmask_b32_e32 v99, v208, v99, vcc
	v_cmp_le_i32_e32 vcc, v119, v162
	s_and_b64 vcc, vcc, s[10:11]
	v_subrev_u32_e32 v119, 54, v14
	v_cndmask_b32_e32 v100, v208, v100, vcc
	v_cmp_le_i32_e32 vcc, v119, v162
	s_and_b64 vcc, vcc, s[10:11]
	v_subrev_u32_e32 v119, 53, v14
	v_cndmask_b32_e32 v101, v208, v101, vcc
	v_cmp_le_i32_e32 vcc, v119, v162
	s_and_b64 vcc, vcc, s[10:11]
	v_subrev_u32_e32 v119, 52, v14
	v_cndmask_b32_e32 v102, v208, v102, vcc
	v_cmp_le_i32_e32 vcc, v119, v162
	s_and_b64 vcc, vcc, s[10:11]
	v_subrev_u32_e32 v119, 47, v14
	v_cndmask_b32_e32 v103, v208, v103, vcc
	v_cmp_le_i32_e32 vcc, v119, v162
	s_and_b64 vcc, vcc, s[10:11]
	v_subrev_u32_e32 v119, 46, v14
	v_cndmask_b32_e32 v104, v208, v104, vcc
	v_cmp_le_i32_e32 vcc, v119, v162
	s_and_b64 vcc, vcc, s[10:11]
	v_subrev_u32_e32 v119, 45, v14
	v_cndmask_b32_e32 v105, v208, v105, vcc
	v_cmp_le_i32_e32 vcc, v119, v162
	s_and_b64 vcc, vcc, s[10:11]
	v_subrev_u32_e32 v119, 44, v14
	v_cndmask_b32_e32 v106, v208, v106, vcc
	v_cmp_le_i32_e32 vcc, v119, v162
	s_and_b64 vcc, vcc, s[10:11]
	v_subrev_u32_e32 v119, 39, v14
	v_cndmask_b32_e32 v107, v208, v107, vcc
	v_cmp_le_i32_e32 vcc, v119, v162
	s_and_b64 vcc, vcc, s[10:11]
	v_subrev_u32_e32 v119, 38, v14
	v_cndmask_b32_e32 v108, v208, v108, vcc
	v_cmp_le_i32_e32 vcc, v119, v162
	s_and_b64 vcc, vcc, s[10:11]
	v_subrev_u32_e32 v119, 37, v14
	v_cndmask_b32_e32 v109, v208, v109, vcc
	v_cmp_le_i32_e32 vcc, v119, v162
	s_and_b64 vcc, vcc, s[10:11]
	v_subrev_u32_e32 v119, 36, v14
	v_cndmask_b32_e32 v110, v208, v110, vcc
	v_cmp_le_i32_e32 vcc, v119, v162
	s_and_b64 vcc, vcc, s[10:11]
	v_subrev_u32_e32 v119, 31, v14
	v_cndmask_b32_e32 v111, v208, v111, vcc
	v_cmp_le_i32_e32 vcc, v119, v162
	s_and_b64 vcc, vcc, s[10:11]
	v_subrev_u32_e32 v119, 30, v14
	v_cndmask_b32_e32 v80, v208, v80, vcc
	v_cmp_le_i32_e32 vcc, v119, v162
	s_and_b64 vcc, vcc, s[10:11]
	v_subrev_u32_e32 v119, 29, v14
	v_cndmask_b32_e32 v81, v208, v81, vcc
	v_cmp_le_i32_e32 vcc, v119, v162
	s_and_b64 vcc, vcc, s[10:11]
	v_subrev_u32_e32 v119, 28, v14
	v_cndmask_b32_e32 v82, v208, v82, vcc
	v_cmp_le_i32_e32 vcc, v119, v162
	s_and_b64 vcc, vcc, s[10:11]
	v_subrev_u32_e32 v119, 23, v14
	v_cndmask_b32_e32 v83, v208, v83, vcc
	v_cmp_le_i32_e32 vcc, v119, v162
	s_and_b64 vcc, vcc, s[10:11]
	v_subrev_u32_e32 v119, 22, v14
	v_cndmask_b32_e32 v84, v208, v84, vcc
	v_cmp_le_i32_e32 vcc, v119, v162
	s_and_b64 vcc, vcc, s[10:11]
	v_subrev_u32_e32 v119, 21, v14
	v_cndmask_b32_e32 v85, v208, v85, vcc
	v_cmp_le_i32_e32 vcc, v119, v162
	s_and_b64 vcc, vcc, s[10:11]
	v_subrev_u32_e32 v119, 20, v14
	v_cndmask_b32_e32 v86, v208, v86, vcc
	v_cmp_le_i32_e32 vcc, v119, v162
	s_and_b64 vcc, vcc, s[10:11]
	v_add_u32_e32 v119, -15, v14
	v_cndmask_b32_e32 v87, v208, v87, vcc
	v_cmp_le_i32_e32 vcc, v119, v162
	s_and_b64 vcc, vcc, s[10:11]
	v_add_u32_e32 v119, -14, v14
	v_cndmask_b32_e32 v88, v208, v88, vcc
	v_cmp_le_i32_e32 vcc, v119, v162
	s_and_b64 vcc, vcc, s[10:11]
	v_add_u32_e32 v119, -13, v14
	v_cndmask_b32_e32 v89, v208, v89, vcc
	v_cmp_le_i32_e32 vcc, v119, v162
	s_and_b64 vcc, vcc, s[10:11]
	v_add_u32_e32 v119, -12, v14
	v_cndmask_b32_e32 v90, v208, v90, vcc
	v_cmp_le_i32_e32 vcc, v119, v162
	s_and_b64 vcc, vcc, s[10:11]
	v_add_u32_e32 v119, -7, v14
	v_cndmask_b32_e32 v91, v208, v91, vcc
	v_cmp_le_i32_e32 vcc, v119, v162
	s_and_b64 vcc, vcc, s[10:11]
	v_add_u32_e32 v119, -6, v14
	v_cndmask_b32_e32 v92, v208, v92, vcc
	v_cmp_le_i32_e32 vcc, v119, v162
	s_and_b64 vcc, vcc, s[10:11]
	v_add_u32_e32 v119, -5, v14
	v_cndmask_b32_e32 v93, v208, v93, vcc
	v_cmp_le_i32_e32 vcc, v119, v162
	s_and_b64 vcc, vcc, s[10:11]
	v_add_u32_e32 v14, -4, v14
	v_cndmask_b32_e32 v94, v208, v94, vcc
	v_cmp_le_i32_e32 vcc, v14, v162
	s_and_b64 vcc, vcc, s[10:11]
	s_nop 0
	v_cndmask_b32_e32 v95, v208, v95, vcc

; #define MFMA(a, b, c) __builtin_amdgcn_mfma_f32_32x32x16_bf16((a), (b), (c), 0, 0, 0)
; DI int crow(int i, int h) { return (i & 3) + 8 * (i >> 2) + 4 * h; }
; template <int DK, int DV, int MODE>
; DI void fa_qk(f32x16 (&S)[2], const bf16x8 (&q)[DK / 16], const char* base, int lr, int lh) {
;   using C = FA<DK, DV>;
; #pragma unroll
;   for (int ks = 0; ks < 2; ++ks) {
; #pragma unroll
;     for (int kk = 0; kk < DK / 16; ++kk) {
;       const bf16x8 kf = *(const bf16x8*)(base + (ks * 32 + lr) * C::KSTR + (kk * 2 + lh) * 16);
;       if (kk == 0) {
; #pragma unroll
;         for (int i = 0; i < 16; ++i) S[ks][i] = 0.f;
;       }
;       S[ks] = MFMA(kf, q[kk], S[ks]);
;     }
;   }
; }
;   using C = FA<DK, DV>;
;   bool selbit = true;
;   bool need_mask = false;
;   if (MODE != 0) need_mask = (kb * 64 + 63 > wave_qmax - 31);
;   if (MODE == 2) selbit = (sel >> kb) & 1ull;
;   if (MODE == 3) need_mask = need_mask || (kb * 64 <= wave_qmax - 512);
;   const float c2 = scale * 1.4426950408889634f;
;   if (need_mask) {
; #pragma unroll
;     for (int ks = 0; ks < 2; ++ks)
; #pragma unroll
;       for (int i = 0; i < 16; ++i) {
;         const int key = kb * 64 + ks * 32 + crow(i, lh);
;         bool valid = key <= qpos;
;         if (MODE == 2) valid = valid && selbit;
;         if (MODE == 3) valid = valid && (qpos - key < 512);
;         S[ks][i] = valid ? S[ks][i] : -1e30f;
;       }
.LBB0_597:
	s_cmp_gt_i32 s7, s20
	s_cbranch_scc1 .LBB0_586
	s_add_i32 s0, s0, 0
	v_add3_u32 v12, s0, v172, v171
	ds_read_b128 v[216:219], v12
	ds_read_b128 v[220:223], v12 offset:32
	ds_read_b128 v[224:227], v12 offset:64
	ds_read_b128 v[228:231], v12 offset:96
	ds_read_b128 v[232:235], v12 offset:4608
	ds_read_b128 v[236:239], v12 offset:4640
	ds_read_b128 v[240:243], v12 offset:4672
	ds_read_b128 v[244:247], v12 offset:4704
	s_add_i32 s1, s7, 31
	s_cmp_gt_i32 s1, s43
	s_cselect_b64 s[8:9], -1, 0
	s_cmp_le_i32 s7, s19
	s_cselect_b64 s[10:11], -1, 0
	s_or_b64 s[8:9], s[8:9], s[10:11]
	s_andn2_b64 vcc, exec, s[8:9]
	s_setprio 1
	s_waitcnt lgkmcnt(7)
	v_mfma_f32_32x32x16_bf16 v[128:143], v[216:219], v[152:155], 0
	s_waitcnt lgkmcnt(6)
	v_mfma_f32_32x32x16_bf16 v[128:143], v[220:223], v[144:147], v[128:143]
	s_waitcnt lgkmcnt(5)
	v_mfma_f32_32x32x16_bf16 v[128:143], v[224:227], v[148:151], v[128:143]
	s_waitcnt lgkmcnt(4)
	v_mfma_f32_32x32x16_bf16 v[128:143], v[228:231], v[156:159], v[128:143]
	s_waitcnt lgkmcnt(3)
	v_mfma_f32_32x32x16_bf16 v[112:127], v[232:235], v[152:155], 0
	s_waitcnt lgkmcnt(2)
	v_mfma_f32_32x32x16_bf16 v[112:127], v[236:239], v[144:147], v[112:127]
	s_waitcnt lgkmcnt(1)
	v_mfma_f32_32x32x16_bf16 v[112:127], v[240:243], v[148:151], v[112:127]
	s_waitcnt lgkmcnt(0)
	v_mfma_f32_32x32x16_bf16 v[112:127], v[244:247], v[156:159], v[112:127]
	s_setprio 0
	v_add3_u32 v247, s0, v175, v172
	v_add_u32_e32 v243, 0x2000, v247
	v_add_u32_e32 v247, 0x3000, v247
	s_cbranch_vccnz .LBB0_600
	v_add_u32_e32 v12, s7, v173
	v_cmp_le_i32_e32 vcc, v12, v162
	v_cmp_gt_i32_e64 s[10:11], v12, v174
	s_and_b64 vcc, vcc, s[10:11]
	v_cndmask_b32_e32 v128, v208, v128, vcc
	v_cmp_lt_i32_e32 vcc, v12, v162
	v_cmp_ge_i32_e64 s[10:11], v12, v174
	s_and_b64 vcc, vcc, s[10:11]
	v_add_u32_e32 v176, 2, v12
	v_cndmask_b32_e32 v129, v208, v129, vcc
	v_cmp_le_i32_e32 vcc, v176, v162
	v_cmp_gt_i32_e64 s[10:11], v176, v174
	s_and_b64 vcc, vcc, s[10:11]
	v_add_u32_e32 v176, 3, v12
	v_cndmask_b32_e32 v130, v208, v130, vcc
	v_cmp_le_i32_e32 vcc, v176, v162
	v_cmp_gt_i32_e64 s[10:11], v176, v174
	s_and_b64 vcc, vcc, s[10:11]
	v_add_u32_e32 v176, 8, v12
	v_cndmask_b32_e32 v131, v208, v131, vcc
	v_cmp_le_i32_e32 vcc, v176, v162
	v_cmp_gt_i32_e64 s[10:11], v176, v174
	s_and_b64 vcc, vcc, s[10:11]
	v_add_u32_e32 v176, 9, v12
	v_cndmask_b32_e32 v132, v208, v132, vcc
	v_cmp_le_i32_e32 vcc, v176, v162
	v_cmp_gt_i32_e64 s[10:11], v176, v174
	s_and_b64 vcc, vcc, s[10:11]
	v_add_u32_e32 v176, 10, v12
	v_cndmask_b32_e32 v133, v208, v133, vcc
	v_cmp_le_i32_e32 vcc, v176, v162
	v_cmp_gt_i32_e64 s[10:11], v176, v174
	s_and_b64 vcc, vcc, s[10:11]
	v_add_u32_e32 v176, 11, v12
	v_cndmask_b32_e32 v134, v208, v134, vcc
	v_cmp_le_i32_e32 vcc, v176, v162
	v_cmp_gt_i32_e64 s[10:11], v176, v174
	s_and_b64 vcc, vcc, s[10:11]
	v_add_u32_e32 v176, 16, v12
	v_cndmask_b32_e32 v135, v208, v135, vcc
	v_cmp_le_i32_e32 vcc, v176, v162
	v_cmp_gt_i32_e64 s[10:11], v176, v174
	s_and_b64 vcc, vcc, s[10:11]
	v_add_u32_e32 v176, 17, v12
	v_cndmask_b32_e32 v136, v208, v136, vcc
	v_cmp_le_i32_e32 vcc, v176, v162
	v_cmp_gt_i32_e64 s[10:11], v176, v174
	s_and_b64 vcc, vcc, s[10:11]
	v_add_u32_e32 v176, 18, v12
	v_cndmask_b32_e32 v137, v208, v137, vcc
	v_cmp_le_i32_e32 vcc, v176, v162
	v_cmp_gt_i32_e64 s[10:11], v176, v174
	s_and_b64 vcc, vcc, s[10:11]
	v_add_u32_e32 v176, 19, v12
	v_cndmask_b32_e32 v138, v208, v138, vcc
	v_cmp_le_i32_e32 vcc, v176, v162
	v_cmp_gt_i32_e64 s[10:11], v176, v174
	s_and_b64 vcc, vcc, s[10:11]
	v_add_u32_e32 v176, 24, v12
	v_cndmask_b32_e32 v139, v208, v139, vcc
	v_cmp_le_i32_e32 vcc, v176, v162
	v_cmp_gt_i32_e64 s[10:11], v176, v174
	s_and_b64 vcc, vcc, s[10:11]
	v_add_u32_e32 v176, 25, v12
	v_cndmask_b32_e32 v140, v208, v140, vcc
	v_cmp_le_i32_e32 vcc, v176, v162
	v_cmp_gt_i32_e64 s[10:11], v176, v174
	s_and_b64 vcc, vcc, s[10:11]
	v_add_u32_e32 v176, 26, v12
	v_cndmask_b32_e32 v141, v208, v141, vcc
	v_cmp_le_i32_e32 vcc, v176, v162
	v_cmp_gt_i32_e64 s[10:11], v176, v174
	s_and_b64 vcc, vcc, s[10:11]
	v_add_u32_e32 v176, 27, v12
	v_cndmask_b32_e32 v142, v208, v142, vcc
	v_cmp_le_i32_e32 vcc, v176, v162
	v_cmp_gt_i32_e64 s[10:11], v176, v174
	s_and_b64 vcc, vcc, s[10:11]
	v_add_u32_e32 v176, 32, v12
	v_cndmask_b32_e32 v143, v208, v143, vcc
	v_cmp_le_i32_e32 vcc, v176, v162
	v_cmp_gt_i32_e64 s[10:11], v176, v174
	s_and_b64 vcc, vcc, s[10:11]
	v_add_u32_e32 v176, 33, v12
	v_cndmask_b32_e32 v112, v208, v112, vcc
	v_cmp_le_i32_e32 vcc, v176, v162
	v_cmp_gt_i32_e64 s[10:11], v176, v174
	s_and_b64 vcc, vcc, s[10:11]
	v_add_u32_e32 v176, 34, v12
	v_cndmask_b32_e32 v113, v208, v113, vcc
	v_cmp_le_i32_e32 vcc, v176, v162
	v_cmp_gt_i32_e64 s[10:11], v176, v174
	s_and_b64 vcc, vcc, s[10:11]
	v_add_u32_e32 v176, 35, v12
	v_cndmask_b32_e32 v114, v208, v114, vcc
	v_cmp_le_i32_e32 vcc, v176, v162
	v_cmp_gt_i32_e64 s[10:11], v176, v174
	s_and_b64 vcc, vcc, s[10:11]
	v_add_u32_e32 v176, 40, v12
	v_cndmask_b32_e32 v115, v208, v115, vcc
	v_cmp_le_i32_e32 vcc, v176, v162
	v_cmp_gt_i32_e64 s[10:11], v176, v174
	s_and_b64 vcc, vcc, s[10:11]
	v_add_u32_e32 v176, 41, v12
	v_cndmask_b32_e32 v116, v208, v116, vcc
	v_cmp_le_i32_e32 vcc, v176, v162
	v_cmp_gt_i32_e64 s[10:11], v176, v174
	s_and_b64 vcc, vcc, s[10:11]
	v_add_u32_e32 v176, 42, v12
	v_cndmask_b32_e32 v117, v208, v117, vcc
	v_cmp_le_i32_e32 vcc, v176, v162
	v_cmp_gt_i32_e64 s[10:11], v176, v174
	s_and_b64 vcc, vcc, s[10:11]
	v_add_u32_e32 v176, 43, v12
	v_cndmask_b32_e32 v118, v208, v118, vcc
	v_cmp_le_i32_e32 vcc, v176, v162
	v_cmp_gt_i32_e64 s[10:11], v176, v174
	s_and_b64 vcc, vcc, s[10:11]
	v_add_u32_e32 v176, 48, v12
	v_cndmask_b32_e32 v119, v208, v119, vcc
	v_cmp_le_i32_e32 vcc, v176, v162
	v_cmp_gt_i32_e64 s[10:11], v176, v174
	s_and_b64 vcc, vcc, s[10:11]
	v_add_u32_e32 v176, 49, v12
	v_cndmask_b32_e32 v120, v208, v120, vcc
	v_cmp_le_i32_e32 vcc, v176, v162
	v_cmp_gt_i32_e64 s[10:11], v176, v174
	s_and_b64 vcc, vcc, s[10:11]
	v_add_u32_e32 v176, 50, v12
	v_cndmask_b32_e32 v121, v208, v121, vcc
	v_cmp_le_i32_e32 vcc, v176, v162
	v_cmp_gt_i32_e64 s[10:11], v176, v174
	s_and_b64 vcc, vcc, s[10:11]
	v_add_u32_e32 v176, 51, v12
	v_cndmask_b32_e32 v122, v208, v122, vcc
	v_cmp_le_i32_e32 vcc, v176, v162
	v_cmp_gt_i32_e64 s[10:11], v176, v174
	s_and_b64 vcc, vcc, s[10:11]
	v_add_u32_e32 v176, 56, v12
	v_cndmask_b32_e32 v123, v208, v123, vcc
	v_cmp_le_i32_e32 vcc, v176, v162
	v_cmp_gt_i32_e64 s[10:11], v176, v174
	s_and_b64 vcc, vcc, s[10:11]
	v_add_u32_e32 v176, 57, v12
	v_cndmask_b32_e32 v124, v208, v124, vcc
	v_cmp_le_i32_e32 vcc, v176, v162
	v_cmp_gt_i32_e64 s[10:11], v176, v174
	s_and_b64 vcc, vcc, s[10:11]
	v_add_u32_e32 v176, 58, v12
	v_cndmask_b32_e32 v125, v208, v125, vcc
	v_cmp_le_i32_e32 vcc, v176, v162
	v_cmp_gt_i32_e64 s[10:11], v176, v174
	s_and_b64 vcc, vcc, s[10:11]
	v_add_u32_e32 v12, 59, v12
	v_cndmask_b32_e32 v126, v208, v126, vcc
	v_cmp_le_i32_e32 vcc, v12, v162
	v_cmp_gt_i32_e64 s[10:11], v12, v174
	s_and_b64 vcc, vcc, s[10:11]
	v_cndmask_b32_e32 v127, v208, v127, vcc
